# combo28: combo27 + GEMM phase prologues issue the six K-tile-1 LDS-DMA loads before the wait+barrier that publishes K-tile 0 (vmcnt(2) -> vmcnt(8)), overlapping the two cold fetches
# baseline (speedup 1.0000x reference)
; #define PG8_STAGE(bufoff, gbase, voff) do { _Pragma("unroll") for (int _i = 0; _i < 2; ++_i) \
;         __builtin_amdgcn_global_load_lds((const unsigned*)((const char*)(gbase) + (voff)[_i]), (PG8_LAS unsigned*)(lds + (bufoff) + ldsw + _i * 8192), 16, 0, 0); } while (0)
; #define PG8_WAIT_V(n) asm volatile("s_waitcnt vmcnt(" #n ")" ::: "memory")
; #define PG8_BAR __builtin_amdgcn_s_barrier()
; template <class Epi, class Sched, bool ALIGN_EPI = false, bool SP2 = false>
; __device__ __forceinline__ void gemm_phase(PG8_LAS unsigned char* lds, const Gemm g, const Sched& S, const Epi& E, const int tid_arg) {
;     ...
;     if constexpr (SP2) {
;         PG8_STAGE(PG8_SB(0, 0), cB, voffB); PG8_STAGE(PG8_SB(0, 1), cB + hstep, voffB); PG8_STAGE(PG8_SA(0, 0), cA, voffA); PG8_STAGE(PG8_SA(0, 1), cA + hstep, voffA);
;         if (wr == 1) PG8_BAR;
;         PG8_WAIT_V(2); PG8_BAR;
;         PG8_STAGE(PG8_SB(1, 0), cB + kstep, voffB); PG8_STAGE(PG8_SA(1, 0), cA + kstep, voffA); PG8_STAGE(PG8_SB(1, 1), cB + hstep + kstep, voffB);
;         PG8_WAIT_V(6); PG8_BAR;
.LBB0_247:
	s_waitcnt lgkmcnt(0)
	s_add_u32 s12, s12, 0x9804000
	s_addc_u32 s13, s13, 0
	s_and_b32 s45, s14, 3
	s_lshl_b32 s46, s15, 6
	s_lshl_b32 s4, s15, 13
	s_add_i32 s47, s39, 0x18000
	s_mov_b64 s[14:15], 0x80
	v_lshl_add_u64 v[6:7], v[6:7], 0, s[14:15]
	s_mov_b32 m0, s47
	s_add_i32 s48, s39, 0x1a000
	s_lshl_b32 s5, s45, 12
	global_load_lds_dwordx4 v[6:7], off
	v_lshl_add_u64 v[4:5], v[4:5], 0, s[14:15]
	s_mov_b32 m0, s48
	s_add_i32 s49, s39, 0x8000
	s_add_i32 s50, s39, 0xa000
	global_load_lds_dwordx4 v[4:5], off
	v_lshl_add_u64 v[0:1], v[0:1], 0, s[14:15]
	s_mov_b32 m0, s49
	s_add_u32 s0, s8, 0x40080
	global_load_lds_dwordx4 v[0:1], off
	v_lshl_add_u64 v[0:1], v[2:3], 0, s[14:15]
	s_mov_b32 m0, s50
	s_addc_u32 s1, s9, 0
	s_add_i32 s51, s39, 0x1c000
	global_load_lds_dwordx4 v[0:1], off
	v_lshl_add_u64 v[0:1], s[0:1], 0, v[130:131]
	s_mov_b32 m0, s51
	s_add_i32 s52, s39, 0x1e000
	global_load_lds_dwordx4 v[0:1], off
	v_lshl_add_u64 v[0:1], s[0:1], 0, v[134:135]
	s_mov_b32 m0, s52
	v_bfe_u32 v164, v8, 4, 2
	global_load_lds_dwordx4 v[0:1], off
	s_waitcnt vmcnt(8)
	s_barrier
	v_and_b32_e32 v163, 15, v8
	v_lshlrev_b32_e32 v0, 4, v164
	v_lshlrev_b32_e32 v1, 2, v8
	v_lshl_or_b32 v0, v163, 6, v0
	v_and_b32_e32 v1, 32, v1
	v_bitop3_b32 v165, v0, s4, v1 bitop3:0xde
	v_bitop3_b32 v0, v0, s5, v1 bitop3:0xde
	v_lshlrev_b32_e32 v1, 14, v12
	v_and_b32_e32 v1, 0xffff8000, v1
	v_lshl_add_u32 v1, v13, 11, v1
	v_and_b32_e32 v2, 1, v12
	v_lshl_or_b32 v1, v2, 6, v1
	v_lshl_add_u32 v136, v14, 1, v1
	v_lshlrev_b32_e32 v1, 14, v9
	v_and_b32_e32 v1, 0xffff8000, v1
	s_waitcnt vmcnt(6)
	s_cmpk_lt_u32 s16, 0x100
	v_lshl_add_u32 v1, v10, 11, v1
	v_and_b32_e32 v2, 1, v9
	s_cselect_b64 s[16:17], -1, 0
	s_lshl_b32 s0, s45, 6
	s_mov_b32 s19, 0
	v_readlane_b32 s4, v251, 0
	v_lshl_or_b32 v1, v2, 6, v1
	s_mov_b32 s53, 0x1c000
	s_ashr_i32 s54, s4, 31
	s_mov_b32 s55, s4
	v_mov_b32_e32 v137, v131
	v_lshl_add_u32 v138, v11, 1, v1
	v_mov_b32_e32 v139, v131
	v_mov_b64_e32 v[140:141], 0x700
	v_mov_b64_e32 v[142:143], 0x6ff
	s_movk_i32 s56, 0xe1
	v_or_b32_e32 v166, 0x10000, v0
	v_add_u32_e32 v167, 0x10400, v0
	v_add_u32_e32 v168, 0x10800, v0
	v_add_u32_e32 v169, 0x10c00, v0
	v_or_b32_e32 v170, 0x14000, v0
	v_add_u32_e32 v171, 0x14400, v0
	v_add_u32_e32 v172, 0x14800, v0
	v_add_u32_e32 v173, 0x14c00, v0
	s_add_i32 s57, s39, 0xc000
	s_add_i32 s58, s39, 0xe000
	v_or_b32_e32 v174, 0x18000, v0
	v_add_u32_e32 v175, 0x18400, v0
	v_add_u32_e32 v176, 0x18800, v0
	v_add_u32_e32 v177, 0x18c00, v0
	v_or_b32_e32 v178, 0x1c000, v0
	v_add_u32_e32 v179, 0x1c400, v0
	v_add_u32_e32 v180, 0x1c800, v0
	v_add_u32_e32 v181, 0x1cc00, v0
	s_movk_i32 s59, 0x140
	v_mov_b32_e32 v182, 0x358637bd
	s_movk_i32 s60, 0x1c00
	s_lshl_b32 s18, s0, 1
	s_mov_b32 s61, 0x38000
	s_mov_b32 s62, 0x54000
	s_mov_b32 s63, 0xe0000
	s_mov_b32 s64, 0xfc000
	s_mov_b32 s65, 0x118000
	s_mov_b32 s66, 0x134000
	s_mov_b32 s67, s19
	s_barrier
	v_readlane_b32 s5, v251, 1
	s_branch .LBB0_250

; #define PG8_STAGE(bufoff, gbase, voff) do { _Pragma("unroll") for (int _i = 0; _i < 2; ++_i) \
;         __builtin_amdgcn_global_load_lds((const unsigned*)((const char*)(gbase) + (voff)[_i]), (PG8_LAS unsigned*)(lds + (bufoff) + ldsw + _i * 8192), 16, 0, 0); } while (0)
; #define PG8_WAIT_V(n) asm volatile("s_waitcnt vmcnt(" #n ")" ::: "memory")
; #define PG8_BAR __builtin_amdgcn_s_barrier()
; template <class Epi, class Sched, bool ALIGN_EPI = false, bool SP2 = false>
; __device__ __forceinline__ void gemm_phase(PG8_LAS unsigned char* lds, const Gemm g, const Sched& S, const Epi& E, const int tid_arg) {
;     ...
;     if constexpr (SP2) {
;         PG8_STAGE(PG8_SB(0, 0), cB, voffB); PG8_STAGE(PG8_SB(0, 1), cB + hstep, voffB); PG8_STAGE(PG8_SA(0, 0), cA, voffA); PG8_STAGE(PG8_SA(0, 1), cA + hstep, voffA);
;         if (wr == 1) PG8_BAR;
;         PG8_WAIT_V(2); PG8_BAR;
;         PG8_STAGE(PG8_SB(1, 0), cB + kstep, voffB); PG8_STAGE(PG8_SA(1, 0), cA + kstep, voffA); PG8_STAGE(PG8_SB(1, 1), cB + hstep + kstep, voffB);
;         PG8_WAIT_V(6); PG8_BAR;
.LBB0_523:
	s_add_u32 s16, s8, 0x18484000
	s_addc_u32 s17, s9, 0
	s_add_u32 s46, s18, 0x1c484000
	s_addc_u32 s47, s19, 0
	s_add_i32 s49, s39, 0x18000
	s_mov_b64 s[20:21], 0x80
	s_and_b32 s8, s0, 3
	v_lshl_add_u64 v[6:7], v[6:7], 0, s[20:21]
	s_mov_b32 m0, s49
	s_add_i32 s50, s39, 0x1a000
	s_lshl_b32 s48, s1, 6
	s_lshl_b32 s9, s1, 13
	s_lshl_b32 s18, s8, 5
	s_lshl_b32 s11, s8, 12
	global_load_lds_dwordx4 v[6:7], off
	v_lshl_add_u64 v[4:5], v[4:5], 0, s[20:21]
	s_mov_b32 m0, s50
	s_add_i32 s51, s39, 0x8000
	s_add_i32 s52, s39, 0xa000
	global_load_lds_dwordx4 v[4:5], off
	v_lshl_add_u64 v[0:1], v[0:1], 0, s[20:21]
	s_mov_b32 m0, s51
	s_add_u32 s0, s12, 0x40080
	global_load_lds_dwordx4 v[0:1], off
	v_lshl_add_u64 v[0:1], v[2:3], 0, s[20:21]
	s_mov_b32 m0, s52
	s_addc_u32 s1, s13, 0
	s_add_i32 s53, s39, 0x1c000
	global_load_lds_dwordx4 v[0:1], off
	v_lshl_add_u64 v[0:1], s[0:1], 0, v[138:139]
	s_mov_b32 m0, s53
	s_add_i32 s54, s39, 0x1e000
	global_load_lds_dwordx4 v[0:1], off
	v_lshl_add_u64 v[0:1], s[0:1], 0, v[142:143]
	s_mov_b32 m0, s54
	v_bfe_u32 v162, v8, 4, 2
	global_load_lds_dwordx4 v[0:1], off
	s_waitcnt vmcnt(8)
	s_barrier
	v_and_b32_e32 v163, 15, v8
	v_lshlrev_b32_e32 v0, 4, v162
	v_lshlrev_b32_e32 v1, 2, v8
	v_lshl_or_b32 v0, v163, 6, v0
	v_and_b32_e32 v1, 32, v1
	v_bitop3_b32 v164, v0, s9, v1 bitop3:0xde
	v_bitop3_b32 v0, v0, s11, v1 bitop3:0xde
	v_lshlrev_b32_e32 v1, 14, v12
	v_and_b32_e32 v1, 0xffff8000, v1
	v_lshl_add_u32 v1, v13, 11, v1
	v_and_b32_e32 v2, 1, v12
	s_cmpk_lt_u32 s22, 0x100
	v_lshl_or_b32 v1, v2, 6, v1
	s_cselect_b64 s[22:23], -1, 0
	s_lshl_b32 s0, s8, 4
	v_lshl_add_u32 v144, v14, 1, v1
	v_lshlrev_b32_e32 v1, 14, v9
	s_or_b32 s55, s0, s48
	v_readlane_b32 s0, v251, 0
	s_lshl_b32 s58, s8, 2
	v_and_b32_e32 v1, 0xffff8000, v1
	s_waitcnt vmcnt(6)
	s_ashr_i32 s56, s0, 31
	s_bitset1_b32 s58, 17
	v_lshl_add_u32 v1, v10, 11, v1
	v_and_b32_e32 v2, 1, v9
	s_mov_b32 s19, 0
	s_cmp_lg_u64 s[6:7], 0
	v_lshl_or_b32 v1, v2, 6, v1
	s_mov_b32 s57, s0
	s_cselect_b64 s[24:25], -1, 0
	v_mov_b32_e32 v145, v139
	v_lshl_add_u32 v146, v11, 1, v1
	v_mov_b32_e32 v147, v139
	v_mov_b64_e32 v[148:149], 0x200
	v_mov_b64_e32 v[150:151], 0x1ff
	v_or_b32_e32 v165, 0x10000, v0
	v_add_u32_e32 v166, 0x10400, v0
	v_add_u32_e32 v167, 0x10800, v0
	v_add_u32_e32 v168, 0x10c00, v0
	v_or_b32_e32 v169, 0x14000, v0
	v_add_u32_e32 v170, 0x14400, v0
	v_add_u32_e32 v171, 0x14800, v0
	v_add_u32_e32 v172, 0x14c00, v0
	s_add_i32 s59, s39, 0xc000
	s_add_i32 s60, s39, 0xe000
	v_or_b32_e32 v173, 0x18000, v0
	v_add_u32_e32 v174, 0x18400, v0
	v_add_u32_e32 v175, 0x18800, v0
	v_add_u32_e32 v176, 0x18c00, v0
	v_or_b32_e32 v177, 0x1c000, v0
	v_add_u32_e32 v178, 0x1c400, v0
	v_add_u32_e32 v179, 0x1c800, v0
	v_add_u32_e32 v180, 0x1cc00, v0
	v_mov_b32_e32 v181, 0x20000
	s_mov_b32 s61, s19
	s_barrier
	v_readlane_b32 s1, v251, 1
	s_branch .LBB0_526

; #define PG8_STAGE(bufoff, gbase, voff) do { _Pragma("unroll") for (int _i = 0; _i < 2; ++_i) \
;         __builtin_amdgcn_global_load_lds((const unsigned*)((const char*)(gbase) + (voff)[_i]), (PG8_LAS unsigned*)(lds + (bufoff) + ldsw + _i * 8192), 16, 0, 0); } while (0)
; #define PG8_WAIT_V(n) asm volatile("s_waitcnt vmcnt(" #n ")" ::: "memory")
; #define PG8_BAR __builtin_amdgcn_s_barrier()
; template <class Epi, class Sched, bool ALIGN_EPI = false, bool SP2 = false>
; __device__ __forceinline__ void gemm_phase(PG8_LAS unsigned char* lds, const Gemm g, const Sched& S, const Epi& E, const int tid_arg) {
;     ...
;     if constexpr (SP2) {
;         PG8_STAGE(PG8_SB(0, 0), cB, voffB); PG8_STAGE(PG8_SB(0, 1), cB + hstep, voffB); PG8_STAGE(PG8_SA(0, 0), cA, voffA); PG8_STAGE(PG8_SA(0, 1), cA + hstep, voffA);
;         if (wr == 1) PG8_BAR;
;         PG8_WAIT_V(2); PG8_BAR;
;         PG8_STAGE(PG8_SB(1, 0), cB + kstep, voffB); PG8_STAGE(PG8_SA(1, 0), cA + kstep, voffA); PG8_STAGE(PG8_SB(1, 1), cB + hstep + kstep, voffB);
;         PG8_WAIT_V(6); PG8_BAR;
.LBB0_679:
	s_waitcnt lgkmcnt(0)
	s_add_u32 s20, s16, 0x9804000
	s_addc_u32 s21, s17, 0
	s_add_u32 s55, s12, 0x17984000
	s_addc_u32 s56, s13, 0
	s_add_u32 s22, s0, 0x1c484000
	s_addc_u32 s23, s1, 0
	s_and_b32 s12, s24, 3
	s_add_i32 s59, s49, 0x18000
	s_mov_b64 s[24:25], 0x80
	v_lshl_add_u64 v[6:7], v[6:7], 0, s[24:25]
	s_mov_b32 m0, s59
	s_add_i32 s60, s49, 0x1a000
	s_lshl_b32 s57, s30, 6
	s_lshl_b32 s13, s30, 13
	s_lshl_b32 s58, s12, 5
	s_lshl_b32 s14, s12, 12
	global_load_lds_dwordx4 v[6:7], off
	v_lshl_add_u64 v[4:5], v[4:5], 0, s[24:25]
	s_mov_b32 m0, s60
	s_add_i32 s61, s49, 0x8000
	s_add_i32 s62, s49, 0xa000
	global_load_lds_dwordx4 v[4:5], off
	v_lshl_add_u64 v[0:1], v[0:1], 0, s[24:25]
	s_mov_b32 m0, s61
	s_add_u32 s0, s10, 0x40080
	global_load_lds_dwordx4 v[0:1], off
	v_lshl_add_u64 v[0:1], v[2:3], 0, s[24:25]
	s_mov_b32 m0, s62
	s_addc_u32 s1, s11, 0
	s_add_i32 s63, s49, 0x1c000
	global_load_lds_dwordx4 v[0:1], off
	v_lshl_add_u64 v[0:1], s[0:1], 0, v[188:189]
	s_mov_b32 m0, s63
	s_add_i32 s64, s49, 0x1e000
	global_load_lds_dwordx4 v[0:1], off
	v_lshl_add_u64 v[0:1], s[0:1], 0, v[192:193]
	s_mov_b32 m0, s64
	v_bfe_u32 v205, v8, 4, 2
	global_load_lds_dwordx4 v[0:1], off
	s_waitcnt vmcnt(8)
	s_barrier
	v_and_b32_e32 v204, 15, v8
	v_lshlrev_b32_e32 v0, 4, v205
	v_lshlrev_b32_e32 v1, 2, v8
	v_lshl_or_b32 v0, v204, 6, v0
	v_and_b32_e32 v1, 32, v1
	v_bitop3_b32 v206, v0, s13, v1 bitop3:0xde
	v_bitop3_b32 v2, v0, s14, v1 bitop3:0xde
	v_and_b32_e32 v1, 1, v14
	v_add3_u32 v0, v16, v17, v18
	v_lshlrev_b32_e32 v1, 6, v1
	v_lshl_or_b32 v0, v0, 11, v1
	s_mov_b64 s[0:1], 0x40080
	s_cmpk_lt_u32 s28, 0x100
	v_lshl_add_u32 v0, v15, 1, v0
	v_mov_b32_e32 v1, v189
	s_cselect_b64 s[26:27], -1, 0
	s_and_b32 s69, s28, 0xffffff00
	s_lshl_b32 s12, s12, 6
	v_lshl_add_u64 v[194:195], v[0:1], 0, s[0:1]
	v_and_b32_e32 v1, 1, v9
	s_or_b32 s66, s12, s69
	s_lshl_b32 s71, s30, 11
	v_add3_u32 v0, v11, v12, v13
	v_lshlrev_b32_e32 v1, 6, v1
	s_waitcnt vmcnt(6)
	s_cmp_gt_i32 s30, 0
	v_lshl_or_b32 v0, v0, 11, v1
	s_cselect_b64 s[28:29], -1, 0
	s_cmp_gt_i32 s30, -2
	v_readlane_b32 s12, v251, 0
	v_lshl_add_u32 v0, v10, 1, v0
	v_mov_b32_e32 v1, v189
	s_movk_i32 s65, 0x100
	s_mov_b32 s16, 0
	s_cselect_b64 s[30:31], -1, 0
	s_ashr_i32 s67, s12, 31
	s_mov_b32 s68, s12
	s_add_i32 s69, s69, 0x24040
	s_add_i32 s70, s71, 0x20000
	s_add_i32 s71, s71, 0x1f800
	v_lshl_add_u64 v[196:197], v[0:1], 0, s[0:1]
	v_or_b32_e32 v207, 0x10000, v2
	v_add_u32_e32 v208, 0x10400, v2
	v_add_u32_e32 v209, 0x10800, v2
	v_add_u32_e32 v210, 0x10c00, v2
	v_or_b32_e32 v211, 0x14000, v2
	v_add_u32_e32 v212, 0x14400, v2
	v_add_u32_e32 v213, 0x14800, v2
	v_add_u32_e32 v214, 0x14c00, v2
	s_add_i32 s72, s49, 0xc000
	s_add_i32 s73, s49, 0xe000
	v_or_b32_e32 v215, 0x18000, v2
	v_add_u32_e32 v216, 0x18400, v2
	v_add_u32_e32 v217, 0x18800, v2
	v_add_u32_e32 v218, 0x18c00, v2
	v_or_b32_e32 v219, 0x1c000, v2
	v_add_u32_e32 v220, 0x1c400, v2
	v_add_u32_e32 v221, 0x1c800, v2
	v_add_u32_e32 v222, 0x1cc00, v2
	s_movk_i32 s74, 0x1600
	v_mov_b32_e32 v223, 0x358637bd
	v_mov_b32_e32 v224, 0x22040
	v_mov_b32_e32 v225, 0x24040
	s_barrier
	v_readlane_b32 s13, v251, 1
	s_branch .LBB0_682

; #define PG8_STAGE(bufoff, gbase, voff) do { _Pragma("unroll") for (int _i = 0; _i < 2; ++_i) \
;         __builtin_amdgcn_global_load_lds((const unsigned*)((const char*)(gbase) + (voff)[_i]), (PG8_LAS unsigned*)(lds + (bufoff) + ldsw + _i * 8192), 16, 0, 0); } while (0)
; #define PG8_WAIT_V(n) asm volatile("s_waitcnt vmcnt(" #n ")" ::: "memory")
; #define PG8_BAR __builtin_amdgcn_s_barrier()
; template <class Epi, class Sched, bool ALIGN_EPI = false, bool SP2 = false>
; __device__ __forceinline__ void gemm_phase(PG8_LAS unsigned char* lds, const Gemm g, const Sched& S, const Epi& E, const int tid_arg) {
;     ...
;     if constexpr (SP2) {
;         PG8_STAGE(PG8_SB(0, 0), cB, voffB); PG8_STAGE(PG8_SB(0, 1), cB + hstep, voffB); PG8_STAGE(PG8_SA(0, 0), cA, voffA); PG8_STAGE(PG8_SA(0, 1), cA + hstep, voffA);
;         if (wr == 1) PG8_BAR;
;         PG8_WAIT_V(2); PG8_BAR;
;         PG8_STAGE(PG8_SB(1, 0), cB + kstep, voffB); PG8_STAGE(PG8_SA(1, 0), cA + kstep, voffA); PG8_STAGE(PG8_SB(1, 1), cB + hstep + kstep, voffB);
;         PG8_WAIT_V(6); PG8_BAR;
.LBB0_857:
	s_waitcnt lgkmcnt(0)
	s_add_u32 s8, s8, 0x18484000
	s_addc_u32 s9, s9, 0
	s_add_u32 s37, s10, 0x1c4c4000
	s_addc_u32 s38, s11, 0
	s_add_i32 s40, s28, 0x18000
	s_mov_b64 s[16:17], 0x80
	s_and_b32 s1, s1, 3
	v_lshl_add_u64 v[6:7], v[6:7], 0, s[16:17]
	s_mov_b32 m0, s40
	s_add_i32 s41, s28, 0x1a000
	s_lshl_b32 s39, s13, 6
	s_lshl_b32 s13, s13, 13
	s_lshl_b32 s14, s1, 5
	s_lshl_b32 s15, s1, 12
	global_load_lds_dwordx4 v[6:7], off
	v_lshl_add_u64 v[4:5], v[4:5], 0, s[16:17]
	s_mov_b32 m0, s41
	s_add_i32 s42, s28, 0x8000
	s_add_i32 s43, s28, 0xa000
	global_load_lds_dwordx4 v[4:5], off
	v_lshl_add_u64 v[0:1], v[0:1], 0, s[16:17]
	s_mov_b32 m0, s42
	s_add_u32 s10, s22, 0xb0080
	global_load_lds_dwordx4 v[0:1], off
	v_lshl_add_u64 v[0:1], v[2:3], 0, s[16:17]
	s_mov_b32 m0, s43
	s_addc_u32 s11, s23, 0
	s_add_i32 s44, s28, 0x1c000
	global_load_lds_dwordx4 v[0:1], off
	v_lshl_add_u64 v[0:1], s[10:11], 0, v[130:131]
	s_mov_b32 m0, s44
	s_add_i32 s45, s28, 0x1e000
	global_load_lds_dwordx4 v[0:1], off
	v_lshl_add_u64 v[0:1], s[10:11], 0, v[134:135]
	s_mov_b32 m0, s45
	v_bfe_u32 v148, v8, 4, 2
	global_load_lds_dwordx4 v[0:1], off
	s_waitcnt vmcnt(8)
	s_barrier
	v_and_b32_e32 v149, 15, v8
	v_lshlrev_b32_e32 v0, 4, v148
	v_lshlrev_b32_e32 v1, 2, v8
	v_lshl_or_b32 v0, v149, 6, v0
	v_and_b32_e32 v1, 32, v1
	s_cmpk_lt_u32 s12, 0x100
	v_bitop3_b32 v150, v0, s13, v1 bitop3:0xde
	v_bitop3_b32 v2, v0, s15, v1 bitop3:0xde
	s_cselect_b64 s[18:19], -1, 0
	s_lshl_b32 s12, s1, 4
	s_lshl_b32 s47, s1, 2
	v_lshrrev_b32_e32 v1, 1, v13
	v_mul_lo_u32 v0, v15, s0
	s_mov_b32 s1, 0xb000
	s_or_b32 s46, s12, s39
	v_mad_u64_u32 v[0:1], s[12:13], v1, s1, v[0:1]
	v_or_b32_e32 v0, v0, v14
	s_mov_b64 s[10:11], 0xb0080
	v_add_lshl_u32 v0, v0, v16, 1
	v_mov_b32_e32 v1, v131
	v_lshl_add_u64 v[136:137], v[0:1], 0, s[10:11]
	v_lshrrev_b32_e32 v1, 1, v9
	v_mul_lo_u32 v0, v10, s0
	v_mad_u64_u32 v[0:1], s[0:1], v1, s1, v[0:1]
	s_waitcnt vmcnt(6)
	v_or_b32_e32 v0, v0, v11
	s_mov_b32 s15, 0
	v_add_lshl_u32 v0, v0, v12, 1
	v_mov_b32_e32 v1, v131
	s_bitset1_b32 s47, 17
	v_lshl_add_u64 v[138:139], v[0:1], 0, s[10:11]
	v_mov_b64_e32 v[140:141], 0x200
	v_mov_b64_e32 v[142:143], 0x1ff
	v_or_b32_e32 v151, 0x10000, v2
	v_add_u32_e32 v152, 0x10400, v2
	v_add_u32_e32 v153, 0x10800, v2
	v_add_u32_e32 v154, 0x10c00, v2
	v_or_b32_e32 v155, 0x14000, v2
	v_add_u32_e32 v156, 0x14400, v2
	v_add_u32_e32 v157, 0x14800, v2
	v_add_u32_e32 v158, 0x14c00, v2
	s_add_i32 s48, s28, 0xc000
	s_add_i32 s49, s28, 0xe000
	v_or_b32_e32 v159, 0x18000, v2
	v_add_u32_e32 v160, 0x18400, v2
	v_add_u32_e32 v161, 0x18800, v2
	v_add_u32_e32 v162, 0x18c00, v2
	v_or_b32_e32 v163, 0x1c000, v2
	v_add_u32_e32 v164, 0x1c400, v2
	v_add_u32_e32 v165, 0x1c800, v2
	v_add_u32_e32 v166, 0x1cc00, v2
	v_mov_b32_e32 v167, 0x20000
	s_mov_b32 s50, s15
	s_barrier
	s_branch .LBB0_860

; #define PG8_STAGE(bufoff, gbase, voff) do { _Pragma("unroll") for (int _i = 0; _i < 2; ++_i) \
;         __builtin_amdgcn_global_load_lds((const unsigned*)((const char*)(gbase) + (voff)[_i]), (PG8_LAS unsigned*)(lds + (bufoff) + ldsw + _i * 8192), 16, 0, 0); } while (0)
; #define PG8_WAIT_V(n) asm volatile("s_waitcnt vmcnt(" #n ")" ::: "memory")
; #define PG8_BAR __builtin_amdgcn_s_barrier()
; template <class Epi, class Sched, bool ALIGN_EPI = false, bool SP2 = false>
; __device__ __forceinline__ void gemm_phase(PG8_LAS unsigned char* lds, const Gemm g, const Sched& S, const Epi& E, const int tid_arg) {
;     ...
;     if constexpr (SP2) {
;         PG8_STAGE(PG8_SB(0, 0), cB, voffB); PG8_STAGE(PG8_SB(0, 1), cB + hstep, voffB); PG8_STAGE(PG8_SA(0, 0), cA, voffA); PG8_STAGE(PG8_SA(0, 1), cA + hstep, voffA);
;         if (wr == 1) PG8_BAR;
;         PG8_WAIT_V(2); PG8_BAR;
;         PG8_STAGE(PG8_SB(1, 0), cB + kstep, voffB); PG8_STAGE(PG8_SA(1, 0), cA + kstep, voffA); PG8_STAGE(PG8_SB(1, 1), cB + hstep + kstep, voffB);
;         PG8_WAIT_V(6); PG8_BAR;
.LBB0_955:
	s_add_u32 s8, s0, 0x1c4c4000
	s_addc_u32 s9, s1, 0
	s_lshl_b32 s0, s12, 5
	s_add_i32 s54, s46, 0x18000
	s_mov_b64 s[12:13], 0x80
	s_and_b32 s18, s0, 0x60
	v_lshl_add_u64 v[6:7], v[6:7], 0, s[12:13]
	s_mov_b32 m0, s54
	s_add_i32 s55, s46, 0x1a000
	s_lshl_b32 s53, s11, 6
	s_lshl_b32 s11, s11, 13
	s_lshl_b32 s15, s18, 7
	global_load_lds_dwordx4 v[6:7], off
	v_lshl_add_u64 v[4:5], v[4:5], 0, s[12:13]
	s_mov_b32 m0, s55
	s_add_i32 s56, s46, 0x8000
	s_add_i32 s57, s46, 0xa000
	global_load_lds_dwordx4 v[4:5], off
	v_lshl_add_u64 v[0:1], v[0:1], 0, s[12:13]
	s_mov_b32 m0, s56
	s_add_u32 s0, s40, 0x40080
	global_load_lds_dwordx4 v[0:1], off
	v_lshl_add_u64 v[0:1], v[2:3], 0, s[12:13]
	s_mov_b32 m0, s57
	s_addc_u32 s1, s41, 0
	s_add_i32 s58, s46, 0x1c000
	global_load_lds_dwordx4 v[0:1], off
	v_lshl_add_u64 v[0:1], s[0:1], 0, v[130:131]
	s_mov_b32 m0, s58
	s_add_i32 s59, s46, 0x1e000
	global_load_lds_dwordx4 v[0:1], off
	v_lshl_add_u64 v[0:1], s[0:1], 0, v[134:135]
	s_mov_b32 m0, s59
	v_bfe_u32 v147, v8, 4, 2
	global_load_lds_dwordx4 v[0:1], off
	s_waitcnt vmcnt(8)
	s_barrier
	v_and_b32_e32 v145, 15, v8
	v_lshlrev_b32_e32 v0, 4, v147
	v_lshlrev_b32_e32 v1, 2, v8
	v_lshl_or_b32 v0, v145, 6, v0
	v_and_b32_e32 v1, 32, v1
	v_bitop3_b32 v149, v0, s11, v1 bitop3:0xde
	v_bitop3_b32 v0, v0, s15, v1 bitop3:0xde
	v_lshlrev_b32_e32 v1, 14, v12
	v_and_b32_e32 v1, 0xffff8000, v1
	v_lshl_add_u32 v1, v13, 11, v1
	v_and_b32_e32 v2, 1, v12
	v_lshl_or_b32 v1, v2, 6, v1
	v_lshl_add_u32 v136, v14, 1, v1
	v_lshlrev_b32_e32 v1, 14, v9
	v_and_b32_e32 v1, 0xffff8000, v1
	s_waitcnt vmcnt(6)
	v_lshl_add_u32 v1, v10, 11, v1
	v_and_b32_e32 v2, 1, v9
	s_cmpk_lt_u32 s14, 0x100
	s_mov_b32 s19, 0
	v_lshl_or_b32 v1, v2, 6, v1
	s_sext_i32_i8 s67, s10
	s_cselect_b64 s[14:15], -1, 0
	v_mov_b32_e32 v137, v131
	v_lshl_add_u32 v138, v11, 1, v1
	v_mov_b32_e32 v139, v131
	v_mov_b64_e32 v[140:141], 0x200
	v_mov_b64_e32 v[142:143], 0x1ff
	v_or_b32_e32 v151, 0x10000, v0
	v_add_u32_e32 v153, 0x10400, v0
	v_add_u32_e32 v155, 0x10800, v0
	v_add_u32_e32 v156, 0x10c00, v0
	v_or_b32_e32 v157, 0x14000, v0
	v_add_u32_e32 v158, 0x14400, v0
	v_add_u32_e32 v159, 0x14800, v0
	v_add_u32_e32 v160, 0x14c00, v0
	s_add_i32 s60, s46, 0xc000
	s_add_i32 s61, s46, 0xe000
	v_or_b32_e32 v161, 0x18000, v0
	v_add_u32_e32 v162, 0x18400, v0
	v_add_u32_e32 v163, 0x18800, v0
	v_add_u32_e32 v164, 0x18c00, v0
	v_or_b32_e32 v165, 0x1c000, v0
	v_add_u32_e32 v166, 0x1c400, v0
	v_add_u32_e32 v167, 0x1c800, v0
	v_add_u32_e32 v168, 0x1cc00, v0
	v_mov_b32_e32 v169, 0x358637bd
	s_lshl_b32 s18, s18, 1
	s_mov_b64 s[20:21], 0x10000
	s_mov_b64 s[22:23], 0x18000
	s_mov_b32 s62, 0x40000
	s_mov_b64 s[24:25], 0x48000
	s_mov_b32 s63, 0x48000
	s_mov_b64 s[26:27], 0x50000
	s_mov_b32 s64, 0x50000
	s_mov_b64 s[28:29], 0x58000
	s_mov_b32 s65, 0x58000
	s_mov_b32 s66, s19
	s_barrier
	s_branch .LBB0_958

; #define PG8_STAGE(bufoff, gbase, voff) do { _Pragma("unroll") for (int _i = 0; _i < 2; ++_i) \
;         __builtin_amdgcn_global_load_lds((const unsigned*)((const char*)(gbase) + (voff)[_i]), (PG8_LAS unsigned*)(lds + (bufoff) + ldsw + _i * 8192), 16, 0, 0); } while (0)
; #define PG8_WAIT_V(n) asm volatile("s_waitcnt vmcnt(" #n ")" ::: "memory")
; #define PG8_BAR __builtin_amdgcn_s_barrier()
; template <class Epi, class Sched, bool ALIGN_EPI = false, bool SP2 = false>
; __device__ __forceinline__ void gemm_phase(PG8_LAS unsigned char* lds, const Gemm g, const Sched& S, const Epi& E, const int tid_arg) {
;     ...
;     if constexpr (SP2) {
;         PG8_STAGE(PG8_SB(0, 0), cB, voffB); PG8_STAGE(PG8_SB(0, 1), cB + hstep, voffB); PG8_STAGE(PG8_SA(0, 0), cA, voffA); PG8_STAGE(PG8_SA(0, 1), cA + hstep, voffA);
;         if (wr == 1) PG8_BAR;
;         PG8_WAIT_V(2); PG8_BAR;
;         PG8_STAGE(PG8_SB(1, 0), cB + kstep, voffB); PG8_STAGE(PG8_SA(1, 0), cA + kstep, voffA); PG8_STAGE(PG8_SB(1, 1), cB + hstep + kstep, voffB);
;         PG8_WAIT_V(6); PG8_BAR;
.LBB0_1031:
	s_add_u32 s20, s0, 0x18484000
	s_addc_u32 s21, s1, 0
	s_add_i32 s44, s36, 0x18000
	s_mov_b64 s[22:23], 0x80
	v_lshl_add_u64 v[8:9], v[8:9], 0, s[22:23]
	s_mov_b32 m0, s44
	s_add_i32 s45, s36, 0x1a000
	global_load_lds_dwordx4 v[8:9], off
	v_lshl_add_u64 v[4:5], v[4:5], 0, s[22:23]
	s_mov_b32 m0, s45
	s_add_i32 s46, s36, 0x8000
	global_load_lds_dwordx4 v[4:5], off
	v_lshl_add_u64 v[4:5], v[6:7], 0, s[22:23]
	s_mov_b32 m0, s46
	s_add_i32 s47, s36, 0xa000
	global_load_lds_dwordx4 v[4:5], off
	v_lshl_add_u64 v[4:5], v[10:11], 0, s[22:23]
	s_mov_b32 m0, s47
	s_add_i32 s48, s36, 0x1c000
	global_load_lds_dwordx4 v[4:5], off
	v_lshl_add_u64 v[2:3], v[2:3], 0, s[22:23]
	s_mov_b32 m0, s48
	s_add_i32 s49, s36, 0x1e000
	global_load_lds_dwordx4 v[2:3], off
	v_lshl_add_u64 v[0:1], v[0:1], 0, s[22:23]
	s_mov_b32 m0, s49
	v_bfe_u32 v148, v12, 4, 2
	global_load_lds_dwordx4 v[0:1], off
	s_waitcnt vmcnt(8)
	s_barrier
	s_lshr_b32 s0, s11, 26
	v_and_b32_e32 v149, 15, v12
	s_add_i32 s0, s10, s0
	v_lshlrev_b32_e32 v0, 4, v148
	v_lshlrev_b32_e32 v1, 2, v12
	s_ashr_i32 s50, s0, 6
	v_lshl_or_b32 v0, v149, 6, v0
	s_lshl_b32 s0, s13, 13
	v_and_b32_e32 v1, 32, v1
	v_bitop3_b32 v150, v0, s0, v1 bitop3:0xde
	s_lshl_b32 s0, s15, 5
	s_and_b32 s24, s0, 0x60
	s_lshl_b32 s0, s24, 7
	v_bitop3_b32 v2, v0, s0, v1 bitop3:0xde
	v_add_u32_e32 v0, v18, v16
	s_lshl_b32 s51, s13, 6
	v_add_lshl_u32 v0, v0, v17, 1
	v_mov_b32_e32 v1, v131
	s_cmp_gt_i32 s10, 63
	v_lshl_add_u64 v[136:137], s[6:7], 0, v[0:1]
	v_add_u32_e32 v0, v15, v13
	s_waitcnt vmcnt(6)
	s_cselect_b64 s[0:1], -1, 0
	s_add_i32 s52, s50, -2
	v_add_lshl_u32 v0, v0, v14, 1
	s_cmpk_lt_u32 s14, 0x100
	s_mov_b32 s25, 0
	v_lshl_add_u64 v[138:139], s[6:7], 0, v[0:1]
	v_cndmask_b32_e64 v0, 0, 1, s[0:1]
	s_sext_i32_i8 s59, s12
	s_cselect_b64 s[26:27], -1, 0
	v_mov_b64_e32 v[140:141], 0x200
	v_mov_b64_e32 v[142:143], 0x1ff
	v_cmp_ne_u32_e64 s[10:11], 1, v0
	v_or_b32_e32 v151, 0x10000, v2
	v_add_u32_e32 v152, 0x10400, v2
	v_add_u32_e32 v153, 0x10800, v2
	v_add_u32_e32 v154, 0x10c00, v2
	v_or_b32_e32 v155, 0x14000, v2
	v_add_u32_e32 v156, 0x14400, v2
	v_add_u32_e32 v157, 0x14800, v2
	v_add_u32_e32 v158, 0x14c00, v2
	s_add_i32 s53, s36, 0xc000
	s_add_i32 s54, s36, 0xe000
	v_or_b32_e32 v159, 0x18000, v2
	v_add_u32_e32 v160, 0x18400, v2
	v_add_u32_e32 v161, 0x18800, v2
	v_add_u32_e32 v162, 0x18c00, v2
	v_or_b32_e32 v163, 0x1c000, v2
	v_add_u32_e32 v164, 0x1c400, v2
	v_add_u32_e32 v165, 0x1c800, v2
	v_add_u32_e32 v166, 0x1cc00, v2
	s_mov_b32 s55, s25
	s_barrier
	s_branch .LBB0_1034

; #define PG8_STAGE(bufoff, gbase, voff) do { _Pragma("unroll") for (int _i = 0; _i < 2; ++_i) \
;         __builtin_amdgcn_global_load_lds((const unsigned*)((const char*)(gbase) + (voff)[_i]), (PG8_LAS unsigned*)(lds + (bufoff) + ldsw + _i * 8192), 16, 0, 0); } while (0)
; #define PG8_WAIT_V(n) asm volatile("s_waitcnt vmcnt(" #n ")" ::: "memory")
; #define PG8_BAR __builtin_amdgcn_s_barrier()
; template <class Epi, class Sched, bool ALIGN_EPI = false, bool SP2 = false>
; __device__ __forceinline__ void gemm_phase(PG8_LAS unsigned char* lds, const Gemm g, const Sched& S, const Epi& E, const int tid_arg) {
;     ...
;     if constexpr (SP2) {
;         PG8_STAGE(PG8_SB(0, 0), cB, voffB); PG8_STAGE(PG8_SB(0, 1), cB + hstep, voffB); PG8_STAGE(PG8_SA(0, 0), cA, voffA); PG8_STAGE(PG8_SA(0, 1), cA + hstep, voffA);
;         if (wr == 1) PG8_BAR;
;         PG8_WAIT_V(2); PG8_BAR;
;         PG8_STAGE(PG8_SB(1, 0), cB + kstep, voffB); PG8_STAGE(PG8_SA(1, 0), cA + kstep, voffA); PG8_STAGE(PG8_SB(1, 1), cB + hstep + kstep, voffB);
;         PG8_WAIT_V(6); PG8_BAR;
.LBB0_1173:
	s_waitcnt lgkmcnt(0)
	s_add_u32 s14, s14, 0x9804000
	s_addc_u32 s15, s15, 0
	s_and_b32 s45, s16, 3
	s_lshl_b32 s46, s17, 6
	s_lshl_b32 s6, s17, 13
	s_add_i32 s47, s39, 0x18000
	s_mov_b64 s[16:17], 0x80
	v_lshl_add_u64 v[6:7], v[6:7], 0, s[16:17]
	s_mov_b32 m0, s47
	s_add_i32 s48, s39, 0x1a000
	s_lshl_b32 s7, s45, 12
	global_load_lds_dwordx4 v[6:7], off
	v_lshl_add_u64 v[4:5], v[4:5], 0, s[16:17]
	s_mov_b32 m0, s48
	s_add_i32 s49, s39, 0x8000
	s_add_i32 s50, s39, 0xa000
	global_load_lds_dwordx4 v[4:5], off
	v_lshl_add_u64 v[0:1], v[0:1], 0, s[16:17]
	s_mov_b32 m0, s49
	s_add_u32 s0, s4, 0x40080
	global_load_lds_dwordx4 v[0:1], off
	v_lshl_add_u64 v[0:1], v[2:3], 0, s[16:17]
	s_mov_b32 m0, s50
	s_addc_u32 s1, s5, 0
	s_add_i32 s51, s39, 0x1c000
	global_load_lds_dwordx4 v[0:1], off
	v_lshl_add_u64 v[0:1], s[0:1], 0, v[130:131]
	s_mov_b32 m0, s51
	s_add_i32 s52, s39, 0x1e000
	global_load_lds_dwordx4 v[0:1], off
	v_lshl_add_u64 v[0:1], s[0:1], 0, v[134:135]
	s_mov_b32 m0, s52
	v_bfe_u32 v164, v8, 4, 2
	global_load_lds_dwordx4 v[0:1], off
	s_waitcnt vmcnt(8)
	s_barrier
	v_and_b32_e32 v163, 15, v8
	v_lshlrev_b32_e32 v0, 4, v164
	v_lshlrev_b32_e32 v1, 2, v8
	v_lshl_or_b32 v0, v163, 6, v0
	v_and_b32_e32 v1, 32, v1
	v_bitop3_b32 v165, v0, s6, v1 bitop3:0xde
	v_bitop3_b32 v0, v0, s7, v1 bitop3:0xde
	v_lshlrev_b32_e32 v1, 14, v12
	v_and_b32_e32 v1, 0xffff8000, v1
	v_lshl_add_u32 v1, v13, 11, v1
	v_and_b32_e32 v2, 1, v12
	v_lshl_or_b32 v1, v2, 6, v1
	v_lshl_add_u32 v136, v14, 1, v1
	v_lshlrev_b32_e32 v1, 14, v9
	v_and_b32_e32 v1, 0xffff8000, v1
	s_waitcnt vmcnt(6)
	s_cmpk_lt_u32 s18, 0x100
	v_lshl_add_u32 v1, v10, 11, v1
	v_and_b32_e32 v2, 1, v9
	s_cselect_b64 s[18:19], -1, 0
	s_lshl_b32 s0, s45, 6
	s_mov_b32 s21, 0
	v_lshl_or_b32 v1, v2, 6, v1
	s_mov_b32 s53, 0x1c000
	v_mov_b32_e32 v137, v131
	v_lshl_add_u32 v138, v11, 1, v1
	v_mov_b32_e32 v139, v131
	v_mov_b64_e32 v[140:141], 0x700
	v_mov_b64_e32 v[142:143], 0x6ff
	s_movk_i32 s54, 0xe1
	v_or_b32_e32 v166, 0x10000, v0
	v_add_u32_e32 v167, 0x10400, v0
	v_add_u32_e32 v168, 0x10800, v0
	v_add_u32_e32 v169, 0x10c00, v0
	v_or_b32_e32 v170, 0x14000, v0
	v_add_u32_e32 v171, 0x14400, v0
	v_add_u32_e32 v172, 0x14800, v0
	v_add_u32_e32 v173, 0x14c00, v0
	s_add_i32 s55, s39, 0xc000
	s_add_i32 s56, s39, 0xe000
	v_or_b32_e32 v174, 0x18000, v0
	v_add_u32_e32 v175, 0x18400, v0
	v_add_u32_e32 v176, 0x18800, v0
	v_add_u32_e32 v177, 0x18c00, v0
	v_or_b32_e32 v178, 0x1c000, v0
	v_add_u32_e32 v179, 0x1c400, v0
	v_add_u32_e32 v180, 0x1c800, v0
	v_add_u32_e32 v181, 0x1cc00, v0
	s_movk_i32 s57, 0x140
	v_mov_b32_e32 v182, 0x358637bd
	s_movk_i32 s58, 0x1c00
	s_lshl_b32 s20, s0, 1
	s_mov_b32 s59, 0x38000
	s_mov_b32 s60, 0x54000
	s_mov_b32 s61, 0xe0000
	s_mov_b32 s62, 0xfc000
	s_mov_b32 s63, 0x118000
	s_mov_b32 s64, 0x134000
	s_mov_b32 s65, s21
	s_barrier
	s_branch .LBB0_1176

; #define PG8_STAGE(bufoff, gbase, voff) do { _Pragma("unroll") for (int _i = 0; _i < 2; ++_i) \
;         __builtin_amdgcn_global_load_lds((const unsigned*)((const char*)(gbase) + (voff)[_i]), (PG8_LAS unsigned*)(lds + (bufoff) + ldsw + _i * 8192), 16, 0, 0); } while (0)
; #define PG8_WAIT_V(n) asm volatile("s_waitcnt vmcnt(" #n ")" ::: "memory")
; #define PG8_BAR __builtin_amdgcn_s_barrier()
; template <class Epi, class Sched, bool ALIGN_EPI = false, bool SP2 = false>
; __device__ __forceinline__ void gemm_phase(PG8_LAS unsigned char* lds, const Gemm g, const Sched& S, const Epi& E, const int tid_arg) {
;     ...
;     if constexpr (SP2) {
;         PG8_STAGE(PG8_SB(0, 0), cB, voffB); PG8_STAGE(PG8_SB(0, 1), cB + hstep, voffB); PG8_STAGE(PG8_SA(0, 0), cA, voffA); PG8_STAGE(PG8_SA(0, 1), cA + hstep, voffA);
;         if (wr == 1) PG8_BAR;
;         PG8_WAIT_V(2); PG8_BAR;
;         PG8_STAGE(PG8_SB(1, 0), cB + kstep, voffB); PG8_STAGE(PG8_SA(1, 0), cA + kstep, voffA); PG8_STAGE(PG8_SB(1, 1), cB + hstep + kstep, voffB);
;         PG8_WAIT_V(6); PG8_BAR;
.LBB0_1449:
	s_add_u32 s10, s6, 0x18484000
	s_addc_u32 s11, s7, 0
	s_add_u32 s42, s12, 0x1c504000
	s_addc_u32 s43, s13, 0
	s_add_i32 s45, s35, 0x18000
	s_mov_b64 s[14:15], 0x80
	s_and_b32 s6, s0, 3
	v_lshl_add_u64 v[6:7], v[6:7], 0, s[14:15]
	s_mov_b32 m0, s45
	s_add_i32 s46, s35, 0x1a000
	s_lshl_b32 s44, s1, 6
	s_lshl_b32 s7, s1, 13
	s_lshl_b32 s12, s6, 5
	s_lshl_b32 s13, s6, 12
	global_load_lds_dwordx4 v[6:7], off
	v_lshl_add_u64 v[4:5], v[4:5], 0, s[14:15]
	s_mov_b32 m0, s46
	s_add_i32 s47, s35, 0x8000
	s_add_i32 s48, s35, 0xa000
	global_load_lds_dwordx4 v[4:5], off
	v_lshl_add_u64 v[0:1], v[0:1], 0, s[14:15]
	s_mov_b32 m0, s47
	s_add_u32 s0, s28, 0x40080
	global_load_lds_dwordx4 v[0:1], off
	v_lshl_add_u64 v[0:1], v[2:3], 0, s[14:15]
	s_mov_b32 m0, s48
	s_addc_u32 s1, s29, 0
	s_add_i32 s49, s35, 0x1c000
	global_load_lds_dwordx4 v[0:1], off
	v_lshl_add_u64 v[0:1], s[0:1], 0, v[130:131]
	s_mov_b32 m0, s49
	s_add_i32 s50, s35, 0x1e000
	global_load_lds_dwordx4 v[0:1], off
	v_lshl_add_u64 v[0:1], s[0:1], 0, v[134:135]
	s_mov_b32 m0, s50
	v_bfe_u32 v148, v8, 4, 2
	global_load_lds_dwordx4 v[0:1], off
	s_waitcnt vmcnt(8)
	s_barrier
	v_and_b32_e32 v149, 15, v8
	v_lshlrev_b32_e32 v0, 4, v148
	v_lshlrev_b32_e32 v1, 2, v8
	v_lshl_or_b32 v0, v149, 6, v0
	v_and_b32_e32 v1, 32, v1
	v_bitop3_b32 v150, v0, s7, v1 bitop3:0xde
	v_bitop3_b32 v0, v0, s13, v1 bitop3:0xde
	v_lshlrev_b32_e32 v1, 14, v12
	v_and_b32_e32 v1, 0xffff8000, v1
	v_lshl_add_u32 v1, v13, 11, v1
	v_and_b32_e32 v2, 1, v12
	v_lshl_or_b32 v1, v2, 6, v1
	v_lshl_add_u32 v136, v14, 1, v1
	v_lshlrev_b32_e32 v1, 14, v9
	v_and_b32_e32 v1, 0xffff8000, v1
	s_waitcnt vmcnt(6)
	s_cmpk_lt_u32 s16, 0x100
	v_lshl_add_u32 v1, v10, 11, v1
	v_and_b32_e32 v2, 1, v9
	s_cselect_b64 s[16:17], -1, 0
	s_mov_b32 s13, 0
	s_lshl_b32 s0, s6, 4
	s_lshl_b32 s52, s6, 2
	v_lshl_or_b32 v1, v2, 6, v1
	s_or_b32 s51, s0, s44
	s_bitset1_b32 s52, 17
	v_mov_b32_e32 v137, v131
	v_lshl_add_u32 v138, v11, 1, v1
	v_mov_b32_e32 v139, v131
	v_mov_b64_e32 v[140:141], 0x200
	v_mov_b64_e32 v[142:143], 0x1ff
	v_or_b32_e32 v151, 0x10000, v0
	v_add_u32_e32 v152, 0x10400, v0
	v_add_u32_e32 v153, 0x10800, v0
	v_add_u32_e32 v154, 0x10c00, v0
	v_or_b32_e32 v155, 0x14000, v0
	v_add_u32_e32 v156, 0x14400, v0
	v_add_u32_e32 v157, 0x14800, v0
	v_add_u32_e32 v158, 0x14c00, v0
	s_add_i32 s53, s35, 0xc000
	s_add_i32 s54, s35, 0xe000
	v_or_b32_e32 v159, 0x18000, v0
	v_add_u32_e32 v160, 0x18400, v0
	v_add_u32_e32 v161, 0x18800, v0
	v_add_u32_e32 v162, 0x18c00, v0
	v_or_b32_e32 v163, 0x1c000, v0
	v_add_u32_e32 v164, 0x1c400, v0
	v_add_u32_e32 v165, 0x1c800, v0
	v_add_u32_e32 v166, 0x1cc00, v0
	v_mov_b32_e32 v167, 0x20000
	s_mov_b32 s55, s13
	s_barrier
	s_branch .LBB0_1452

; #define PG8_STAGE(bufoff, gbase, voff) do { _Pragma("unroll") for (int _i = 0; _i < 2; ++_i) \
;         __builtin_amdgcn_global_load_lds((const unsigned*)((const char*)(gbase) + (voff)[_i]), (PG8_LAS unsigned*)(lds + (bufoff) + ldsw + _i * 8192), 16, 0, 0); } while (0)
; #define PG8_WAIT_V(n) asm volatile("s_waitcnt vmcnt(" #n ")" ::: "memory")
; #define PG8_BAR __builtin_amdgcn_s_barrier()
; template <class Epi, class Sched, bool ALIGN_EPI = false, bool SP2 = false>
; __device__ __forceinline__ void gemm_phase(PG8_LAS unsigned char* lds, const Gemm g, const Sched& S, const Epi& E, const int tid_arg) {
;     ...
;     if constexpr (SP2) {
;         PG8_STAGE(PG8_SB(0, 0), cB, voffB); PG8_STAGE(PG8_SB(0, 1), cB + hstep, voffB); PG8_STAGE(PG8_SA(0, 0), cA, voffA); PG8_STAGE(PG8_SA(0, 1), cA + hstep, voffA);
;         if (wr == 1) PG8_BAR;
;         PG8_WAIT_V(2); PG8_BAR;
;         PG8_STAGE(PG8_SB(1, 0), cB + kstep, voffB); PG8_STAGE(PG8_SA(1, 0), cA + kstep, voffA); PG8_STAGE(PG8_SB(1, 1), cB + hstep + kstep, voffB);
;         PG8_WAIT_V(6); PG8_BAR;
.LBB0_1541:
	s_waitcnt lgkmcnt(0)
	s_add_u32 s16, s16, 0x9804000
	s_addc_u32 s17, s17, 0
	s_add_u32 s52, s18, 0x10800
	s_addc_u32 s53, s19, 0
	s_add_u32 s54, s10, 0x5800
	s_addc_u32 s55, s11, 0
	s_add_u32 s56, s8, 0x17984000
	s_addc_u32 s57, s9, 0
	s_add_u32 s18, s0, 0x1c504000
	s_addc_u32 s19, s1, 0
	s_and_b32 s8, s20, 3
	s_add_i32 s60, s46, 0x18000
	s_mov_b64 s[20:21], 0x80
	v_lshl_add_u64 v[6:7], v[6:7], 0, s[20:21]
	s_mov_b32 m0, s60
	s_add_i32 s61, s46, 0x1a000
	s_lshl_b32 s58, s26, 6
	s_lshl_b32 s9, s26, 13
	s_lshl_b32 s59, s8, 5
	s_lshl_b32 s10, s8, 12
	global_load_lds_dwordx4 v[6:7], off
	v_lshl_add_u64 v[4:5], v[4:5], 0, s[20:21]
	s_mov_b32 m0, s61
	s_add_i32 s62, s46, 0x8000
	s_add_i32 s63, s46, 0xa000
	global_load_lds_dwordx4 v[4:5], off
	v_lshl_add_u64 v[0:1], v[0:1], 0, s[20:21]
	s_mov_b32 m0, s62
	s_add_u32 s0, s6, 0x40080
	global_load_lds_dwordx4 v[0:1], off
	v_lshl_add_u64 v[0:1], v[2:3], 0, s[20:21]
	s_mov_b32 m0, s63
	s_addc_u32 s1, s7, 0
	s_add_i32 s64, s46, 0x1c000
	global_load_lds_dwordx4 v[0:1], off
	v_lshl_add_u64 v[0:1], s[0:1], 0, v[188:189]
	s_mov_b32 m0, s64
	s_add_i32 s65, s46, 0x1e000
	global_load_lds_dwordx4 v[0:1], off
	v_lshl_add_u64 v[0:1], s[0:1], 0, v[192:193]
	s_mov_b32 m0, s65
	v_bfe_u32 v205, v8, 4, 2
	global_load_lds_dwordx4 v[0:1], off
	s_waitcnt vmcnt(8)
	s_barrier
	v_and_b32_e32 v204, 15, v8
	v_lshlrev_b32_e32 v0, 4, v205
	v_lshlrev_b32_e32 v1, 2, v8
	v_lshl_or_b32 v0, v204, 6, v0
	v_and_b32_e32 v1, 32, v1
	v_bitop3_b32 v206, v0, s9, v1 bitop3:0xde
	v_bitop3_b32 v2, v0, s10, v1 bitop3:0xde
	v_and_b32_e32 v1, 1, v14
	v_add3_u32 v0, v16, v17, v18
	v_lshlrev_b32_e32 v1, 6, v1
	v_lshl_or_b32 v0, v0, 11, v1
	s_mov_b64 s[0:1], 0x40080
	s_cmpk_lt_u32 s24, 0x100
	v_lshl_add_u32 v0, v15, 1, v0
	v_mov_b32_e32 v1, v189
	s_cselect_b64 s[22:23], -1, 0
	s_and_b32 s67, s24, 0xffffff00
	s_lshl_b32 s8, s8, 6
	v_lshl_add_u64 v[194:195], v[0:1], 0, s[0:1]
	v_and_b32_e32 v1, 1, v9
	s_or_b32 s66, s8, s67
	s_lshl_b32 s69, s26, 11
	v_add3_u32 v0, v11, v12, v13
	v_lshlrev_b32_e32 v1, 6, v1
	s_waitcnt vmcnt(6)
	s_cmp_gt_i32 s26, 0
	v_lshl_or_b32 v0, v0, 11, v1
	s_cselect_b64 s[24:25], -1, 0
	s_cmp_gt_i32 s26, -2
	v_lshl_add_u32 v0, v10, 1, v0
	v_mov_b32_e32 v1, v189
	s_movk_i32 s33, 0x100
	s_mov_b32 s12, 0
	s_cselect_b64 s[26:27], -1, 0
	s_add_i32 s67, s67, 0x24040
	s_add_i32 s68, s69, 0x20000
	s_add_i32 s69, s69, 0x1f800
	v_lshl_add_u64 v[196:197], v[0:1], 0, s[0:1]
	s_movk_i32 s70, 0x161
	v_or_b32_e32 v207, 0x10000, v2
	v_add_u32_e32 v208, 0x10400, v2
	v_add_u32_e32 v209, 0x10800, v2
	v_add_u32_e32 v210, 0x10c00, v2
	v_or_b32_e32 v211, 0x14000, v2
	v_add_u32_e32 v212, 0x14400, v2
	v_add_u32_e32 v213, 0x14800, v2
	v_add_u32_e32 v214, 0x14c00, v2
	s_add_i32 s71, s46, 0xc000
	s_add_i32 s72, s46, 0xe000
	v_or_b32_e32 v215, 0x18000, v2
	v_add_u32_e32 v216, 0x18400, v2
	v_add_u32_e32 v217, 0x18800, v2
	v_add_u32_e32 v218, 0x18c00, v2
	v_or_b32_e32 v219, 0x1c000, v2
	v_add_u32_e32 v220, 0x1c400, v2
	v_add_u32_e32 v221, 0x1c800, v2
	v_add_u32_e32 v222, 0x1cc00, v2
	s_movk_i32 s73, 0x1600
	v_mov_b32_e32 v223, 0x358637bd
	v_mov_b32_e32 v224, 0x22040
	v_mov_b32_e32 v225, 0x24040
	s_barrier
	s_branch .LBB0_1544

; #define PG8_STAGE(bufoff, gbase, voff) do { _Pragma("unroll") for (int _i = 0; _i < 2; ++_i) \
;         __builtin_amdgcn_global_load_lds((const unsigned*)((const char*)(gbase) + (voff)[_i]), (PG8_LAS unsigned*)(lds + (bufoff) + ldsw + _i * 8192), 16, 0, 0); } while (0)
; #define PG8_WAIT_V(n) asm volatile("s_waitcnt vmcnt(" #n ")" ::: "memory")
; #define PG8_BAR __builtin_amdgcn_s_barrier()
; template <class Epi, class Sched, bool ALIGN_EPI = false, bool SP2 = false>
; __device__ __forceinline__ void gemm_phase(PG8_LAS unsigned char* lds, const Gemm g, const Sched& S, const Epi& E, const int tid_arg) {
;     ...
;     if constexpr (SP2) {
;         PG8_STAGE(PG8_SB(0, 0), cB, voffB); PG8_STAGE(PG8_SB(0, 1), cB + hstep, voffB); PG8_STAGE(PG8_SA(0, 0), cA, voffA); PG8_STAGE(PG8_SA(0, 1), cA + hstep, voffA);
;         if (wr == 1) PG8_BAR;
;         PG8_WAIT_V(2); PG8_BAR;
;         PG8_STAGE(PG8_SB(1, 0), cB + kstep, voffB); PG8_STAGE(PG8_SA(1, 0), cA + kstep, voffA); PG8_STAGE(PG8_SB(1, 1), cB + hstep + kstep, voffB);
;         PG8_WAIT_V(6); PG8_BAR;
.LBB0_1719:
	s_waitcnt lgkmcnt(0)
	s_add_u32 s12, s6, 0x18484000
	s_addc_u32 s13, s7, 0
	s_add_u32 s37, s8, 0x1c544000
	s_addc_u32 s38, s9, 0
	s_add_i32 s40, s28, 0x18000
	s_mov_b64 s[16:17], 0x80
	s_and_b32 s1, s1, 3
	v_lshl_add_u64 v[6:7], v[6:7], 0, s[16:17]
	s_mov_b32 m0, s40
	s_add_i32 s41, s28, 0x1a000
	s_lshl_b32 s39, s14, 6
	s_lshl_b32 s8, s14, 13
	s_lshl_b32 s14, s1, 5
	s_lshl_b32 s9, s1, 12
	global_load_lds_dwordx4 v[6:7], off
	v_lshl_add_u64 v[4:5], v[4:5], 0, s[16:17]
	s_mov_b32 m0, s41
	s_add_i32 s42, s28, 0x8000
	s_add_i32 s43, s28, 0xa000
	global_load_lds_dwordx4 v[4:5], off
	v_lshl_add_u64 v[0:1], v[0:1], 0, s[16:17]
	s_mov_b32 m0, s42
	s_add_u32 s6, s22, 0xb0080
	global_load_lds_dwordx4 v[0:1], off
	v_lshl_add_u64 v[0:1], v[2:3], 0, s[16:17]
	s_mov_b32 m0, s43
	s_addc_u32 s7, s23, 0
	s_add_i32 s44, s28, 0x1c000
	global_load_lds_dwordx4 v[0:1], off
	v_lshl_add_u64 v[0:1], s[6:7], 0, v[130:131]
	s_mov_b32 m0, s44
	s_add_i32 s45, s28, 0x1e000
	global_load_lds_dwordx4 v[0:1], off
	v_lshl_add_u64 v[0:1], s[6:7], 0, v[134:135]
	s_mov_b32 m0, s45
	v_bfe_u32 v148, v8, 4, 2
	global_load_lds_dwordx4 v[0:1], off
	s_waitcnt vmcnt(8)
	s_barrier
	v_and_b32_e32 v149, 15, v8
	v_lshlrev_b32_e32 v0, 4, v148
	v_lshlrev_b32_e32 v1, 2, v8
	v_lshl_or_b32 v0, v149, 6, v0
	v_and_b32_e32 v1, 32, v1
	s_cmpk_lt_u32 s15, 0x100
	v_bitop3_b32 v150, v0, s8, v1 bitop3:0xde
	v_bitop3_b32 v2, v0, s9, v1 bitop3:0xde
	s_cselect_b64 s[18:19], -1, 0
	s_lshl_b32 s8, s1, 4
	s_lshl_b32 s47, s1, 2
	v_lshrrev_b32_e32 v1, 1, v13
	v_mul_lo_u32 v0, v15, s0
	s_mov_b32 s1, 0xb000
	s_or_b32 s46, s8, s39
	v_mad_u64_u32 v[0:1], s[8:9], v1, s1, v[0:1]
	v_or_b32_e32 v0, v0, v14
	s_mov_b64 s[6:7], 0xb0080
	v_add_lshl_u32 v0, v0, v16, 1
	v_mov_b32_e32 v1, v131
	v_lshl_add_u64 v[136:137], v[0:1], 0, s[6:7]
	v_lshrrev_b32_e32 v1, 1, v9
	v_mul_lo_u32 v0, v10, s0
	v_mad_u64_u32 v[0:1], s[0:1], v1, s1, v[0:1]
	s_waitcnt vmcnt(6)
	v_or_b32_e32 v0, v0, v11
	s_mov_b32 s15, 0
	v_add_lshl_u32 v0, v0, v12, 1
	v_mov_b32_e32 v1, v131
	s_bitset1_b32 s47, 17
	v_lshl_add_u64 v[138:139], v[0:1], 0, s[6:7]
	v_mov_b64_e32 v[140:141], 0x200
	v_mov_b64_e32 v[142:143], 0x1ff
	v_or_b32_e32 v151, 0x10000, v2
	v_add_u32_e32 v152, 0x10400, v2
	v_add_u32_e32 v153, 0x10800, v2
	v_add_u32_e32 v154, 0x10c00, v2
	v_or_b32_e32 v155, 0x14000, v2
	v_add_u32_e32 v156, 0x14400, v2
	v_add_u32_e32 v157, 0x14800, v2
	v_add_u32_e32 v158, 0x14c00, v2
	s_add_i32 s48, s28, 0xc000
	s_add_i32 s49, s28, 0xe000
	v_or_b32_e32 v159, 0x18000, v2
	v_add_u32_e32 v160, 0x18400, v2
	v_add_u32_e32 v161, 0x18800, v2
	v_add_u32_e32 v162, 0x18c00, v2
	v_or_b32_e32 v163, 0x1c000, v2
	v_add_u32_e32 v164, 0x1c400, v2
	v_add_u32_e32 v165, 0x1c800, v2
	v_add_u32_e32 v166, 0x1cc00, v2
	v_mov_b32_e32 v167, 0x20000
	s_mov_b32 s50, s15
	s_barrier
	s_branch .LBB0_1722

; #define PG8_STAGE(bufoff, gbase, voff) do { _Pragma("unroll") for (int _i = 0; _i < 2; ++_i) \
;         __builtin_amdgcn_global_load_lds((const unsigned*)((const char*)(gbase) + (voff)[_i]), (PG8_LAS unsigned*)(lds + (bufoff) + ldsw + _i * 8192), 16, 0, 0); } while (0)
; #define PG8_WAIT_V(n) asm volatile("s_waitcnt vmcnt(" #n ")" ::: "memory")
; #define PG8_BAR __builtin_amdgcn_s_barrier()
; template <class Epi, class Sched, bool ALIGN_EPI = false, bool SP2 = false>
; __device__ __forceinline__ void gemm_phase(PG8_LAS unsigned char* lds, const Gemm g, const Sched& S, const Epi& E, const int tid_arg) {
;     ...
;     if constexpr (SP2) {
;         PG8_STAGE(PG8_SB(0, 0), cB, voffB); PG8_STAGE(PG8_SB(0, 1), cB + hstep, voffB); PG8_STAGE(PG8_SA(0, 0), cA, voffA); PG8_STAGE(PG8_SA(0, 1), cA + hstep, voffA);
;         if (wr == 1) PG8_BAR;
;         PG8_WAIT_V(2); PG8_BAR;
;         PG8_STAGE(PG8_SB(1, 0), cB + kstep, voffB); PG8_STAGE(PG8_SA(1, 0), cA + kstep, voffA); PG8_STAGE(PG8_SB(1, 1), cB + hstep + kstep, voffB);
;         PG8_WAIT_V(6); PG8_BAR;
.LBB0_1817:
	s_add_u32 s14, s0, 0x1c544000
	s_addc_u32 s15, s1, 0
	s_lshl_b32 s0, s16, 5
	s_add_i32 s59, s50, 0x18000
	s_mov_b64 s[16:17], 0x80
	s_and_b32 s20, s0, 0x60
	v_lshl_add_u64 v[6:7], v[6:7], 0, s[16:17]
	s_mov_b32 m0, s59
	s_add_i32 s60, s50, 0x1a000
	s_lshl_b32 s58, s7, 6
	s_lshl_b32 s7, s7, 13
	s_lshl_b32 s19, s20, 7
	global_load_lds_dwordx4 v[6:7], off
	v_lshl_add_u64 v[4:5], v[4:5], 0, s[16:17]
	s_mov_b32 m0, s60
	s_add_i32 s61, s50, 0x8000
	s_add_i32 s62, s50, 0xa000
	global_load_lds_dwordx4 v[4:5], off
	v_lshl_add_u64 v[0:1], v[0:1], 0, s[16:17]
	s_mov_b32 m0, s61
	s_add_u32 s0, s44, 0x40080
	global_load_lds_dwordx4 v[0:1], off
	v_lshl_add_u64 v[0:1], v[2:3], 0, s[16:17]
	s_mov_b32 m0, s62
	s_addc_u32 s1, s45, 0
	s_add_i32 s63, s50, 0x1c000
	global_load_lds_dwordx4 v[0:1], off
	v_lshl_add_u64 v[0:1], s[0:1], 0, v[130:131]
	s_mov_b32 m0, s63
	s_add_i32 s64, s50, 0x1e000
	global_load_lds_dwordx4 v[0:1], off
	v_lshl_add_u64 v[0:1], s[0:1], 0, v[134:135]
	s_mov_b32 m0, s64
	v_bfe_u32 v147, v8, 4, 2
	global_load_lds_dwordx4 v[0:1], off
	s_waitcnt vmcnt(8)
	s_barrier
	v_and_b32_e32 v145, 15, v8
	v_lshlrev_b32_e32 v0, 4, v147
	v_lshlrev_b32_e32 v1, 2, v8
	v_lshl_or_b32 v0, v145, 6, v0
	v_and_b32_e32 v1, 32, v1
	v_bitop3_b32 v149, v0, s7, v1 bitop3:0xde
	v_bitop3_b32 v0, v0, s19, v1 bitop3:0xde
	v_lshlrev_b32_e32 v1, 14, v12
	v_and_b32_e32 v1, 0xffff8000, v1
	v_lshl_add_u32 v1, v13, 11, v1
	v_and_b32_e32 v2, 1, v12
	v_lshl_or_b32 v1, v2, 6, v1
	v_lshl_add_u32 v136, v14, 1, v1
	v_lshlrev_b32_e32 v1, 14, v9
	v_and_b32_e32 v1, 0xffff8000, v1
	s_waitcnt vmcnt(6)
	v_lshl_add_u32 v1, v10, 11, v1
	v_and_b32_e32 v2, 1, v9
	s_cmpk_lt_u32 s18, 0x100
	s_mov_b32 s21, 0
	v_lshl_or_b32 v1, v2, 6, v1
	s_sext_i32_i8 s74, s6
	s_mov_b32 s65, 0x18000
	s_mov_b32 s66, 0x8000
	s_cselect_b64 s[18:19], -1, 0
	v_mov_b32_e32 v137, v131
	v_lshl_add_u32 v138, v11, 1, v1
	v_mov_b32_e32 v139, v131
	v_mov_b64_e32 v[140:141], 0x200
	v_mov_b64_e32 v[142:143], 0x1ff
	v_or_b32_e32 v151, 0x10000, v0
	v_add_u32_e32 v153, 0x10400, v0
	v_add_u32_e32 v155, 0x10800, v0
	v_add_u32_e32 v156, 0x10c00, v0
	v_or_b32_e32 v157, 0x14000, v0
	v_add_u32_e32 v158, 0x14400, v0
	v_add_u32_e32 v159, 0x14800, v0
	v_add_u32_e32 v160, 0x14c00, v0
	s_add_i32 s67, s50, 0xc000
	s_add_i32 s68, s50, 0xe000
	v_or_b32_e32 v161, 0x18000, v0
	v_add_u32_e32 v162, 0x18400, v0
	v_add_u32_e32 v163, 0x18800, v0
	v_add_u32_e32 v164, 0x18c00, v0
	v_or_b32_e32 v165, 0x1c000, v0
	v_add_u32_e32 v166, 0x1c400, v0
	v_add_u32_e32 v167, 0x1c800, v0
	v_add_u32_e32 v168, 0x1cc00, v0
	v_mov_b32_e32 v169, 0x358637bd
	s_lshl_b32 s20, s20, 1
	s_mov_b64 s[22:23], 0x8000
	s_mov_b64 s[24:25], 0x10000
	s_mov_b64 s[26:27], 0x18000
	s_mov_b32 s69, 0x40000
	s_mov_b64 s[28:29], 0x48000
	s_mov_b32 s70, 0x48000
	s_mov_b64 s[30:31], 0x50000
	s_mov_b32 s71, 0x50000
	s_mov_b64 s[34:35], 0x58000
	s_mov_b32 s72, 0x58000
	s_mov_b32 s73, s21
	s_barrier
	s_branch .LBB0_1820

; #define PG8_STAGE(bufoff, gbase, voff) do { _Pragma("unroll") for (int _i = 0; _i < 2; ++_i) \
;         __builtin_amdgcn_global_load_lds((const unsigned*)((const char*)(gbase) + (voff)[_i]), (PG8_LAS unsigned*)(lds + (bufoff) + ldsw + _i * 8192), 16, 0, 0); } while (0)
; #define PG8_WAIT_V(n) asm volatile("s_waitcnt vmcnt(" #n ")" ::: "memory")
; #define PG8_BAR __builtin_amdgcn_s_barrier()
; template <class Epi, class Sched, bool ALIGN_EPI = false, bool SP2 = false>
; __device__ __forceinline__ void gemm_phase(PG8_LAS unsigned char* lds, const Gemm g, const Sched& S, const Epi& E, const int tid_arg) {
;     ...
;     if constexpr (SP2) {
;         PG8_STAGE(PG8_SB(0, 0), cB, voffB); PG8_STAGE(PG8_SB(0, 1), cB + hstep, voffB); PG8_STAGE(PG8_SA(0, 0), cA, voffA); PG8_STAGE(PG8_SA(0, 1), cA + hstep, voffA);
;         if (wr == 1) PG8_BAR;
;         PG8_WAIT_V(2); PG8_BAR;
;         PG8_STAGE(PG8_SB(1, 0), cB + kstep, voffB); PG8_STAGE(PG8_SA(1, 0), cA + kstep, voffA); PG8_STAGE(PG8_SB(1, 1), cB + hstep + kstep, voffB);
;         PG8_WAIT_V(6); PG8_BAR;
.LBB0_1896:
	s_add_u32 s18, s6, 0x18484000
	s_addc_u32 s19, s7, 0
	s_add_i32 s49, s41, 0x18000
	s_mov_b64 s[20:21], 0x80
	v_lshl_add_u64 v[8:9], v[8:9], 0, s[20:21]
	s_mov_b32 m0, s49
	s_add_i32 s50, s41, 0x1a000
	global_load_lds_dwordx4 v[8:9], off
	v_lshl_add_u64 v[4:5], v[4:5], 0, s[20:21]
	s_mov_b32 m0, s50
	s_add_i32 s51, s41, 0x8000
	global_load_lds_dwordx4 v[4:5], off
	v_lshl_add_u64 v[4:5], v[6:7], 0, s[20:21]
	s_mov_b32 m0, s51
	s_add_i32 s52, s41, 0xa000
	global_load_lds_dwordx4 v[4:5], off
	v_lshl_add_u64 v[4:5], v[10:11], 0, s[20:21]
	s_mov_b32 m0, s52
	s_add_i32 s53, s41, 0x1c000
	global_load_lds_dwordx4 v[4:5], off
	v_lshl_add_u64 v[2:3], v[2:3], 0, s[20:21]
	s_mov_b32 m0, s53
	s_add_i32 s54, s41, 0x1e000
	global_load_lds_dwordx4 v[2:3], off
	v_lshl_add_u64 v[0:1], v[0:1], 0, s[20:21]
	s_mov_b32 m0, s54
	v_bfe_u32 v154, v12, 4, 2
	global_load_lds_dwordx4 v[0:1], off
	s_waitcnt vmcnt(8)
	s_barrier
	v_and_b32_e32 v155, 15, v12
	v_lshlrev_b32_e32 v0, 4, v154
	v_lshlrev_b32_e32 v1, 2, v12
	s_lshl_b32 s56, s0, 6
	v_lshl_or_b32 v0, v155, 6, v0
	s_lshl_b32 s0, s0, 13
	v_and_b32_e32 v1, 32, v1
	v_bitop3_b32 v156, v0, s0, v1 bitop3:0xde
	s_lshl_b32 s0, s1, 5
	s_lshr_b32 s5, s5, 26
	s_and_b32 s22, s0, 0x60
	s_add_i32 s5, s4, s5
	s_lshl_b32 s0, s22, 7
	s_ashr_i32 s55, s5, 6
	v_bitop3_b32 v2, v0, s0, v1 bitop3:0xde
	v_add_u32_e32 v0, v18, v16
	s_cmp_gt_i32 s4, 63
	v_add_lshl_u32 v0, v0, v17, 1
	v_mov_b32_e32 v1, v131
	s_cselect_b64 s[0:1], -1, 0
	s_add_i32 s57, s55, -2
	v_lshl_add_u64 v[136:137], s[12:13], 0, v[0:1]
	v_add_u32_e32 v0, v15, v13
	s_waitcnt vmcnt(6)
	s_cmpk_lt_u32 s23, 0x100
	v_add_lshl_u32 v0, v0, v14, 1
	s_cselect_b64 s[24:25], -1, 0
	s_mov_b32 s23, 0
	s_cmp_lg_u64 s[10:11], 0
	v_lshl_add_u64 v[138:139], s[12:13], 0, v[0:1]
	v_cndmask_b32_e64 v0, 0, 1, s[0:1]
	s_cselect_b64 s[26:27], -1, 0
	v_mov_b64_e32 v[140:141], 0x200
	v_mov_b64_e32 v[142:143], 0x1ff
	v_cmp_ne_u32_e64 s[0:1], 1, v0
	v_or_b32_e32 v157, 0x10000, v2
	v_add_u32_e32 v158, 0x10400, v2
	v_add_u32_e32 v159, 0x10800, v2
	v_add_u32_e32 v160, 0x10c00, v2
	v_or_b32_e32 v161, 0x14000, v2
	v_add_u32_e32 v162, 0x14400, v2
	v_add_u32_e32 v163, 0x14800, v2
	v_add_u32_e32 v164, 0x14c00, v2
	s_add_i32 s58, s41, 0xc000
	s_add_i32 s59, s41, 0xe000
	v_or_b32_e32 v165, 0x18000, v2
	v_add_u32_e32 v166, 0x18400, v2
	v_add_u32_e32 v167, 0x18800, v2
	v_add_u32_e32 v168, 0x18c00, v2
	v_or_b32_e32 v169, 0x1c000, v2
	v_add_u32_e32 v170, 0x1c400, v2
	v_add_u32_e32 v171, 0x1c800, v2
	v_add_u32_e32 v172, 0x1cc00, v2
	s_mov_b32 s60, s23
	s_barrier
	s_branch .LBB0_1899
